# k4 + GEMM MMA blocks: MFMAs reordered so consecutive MFMAs share an operand (snake order over the fragment grid)
# speedup vs baseline: 1.0058x; 1.0036x over previous
.LBB0_181:
	s_waitcnt lgkmcnt(0)
	ds_read_b128 v[152:155], v176
	ds_read_b128 v[156:159], v176 offset:1024
	ds_read_b128 v[160:163], v176 offset:2048
	ds_read_b128 v[164:167], v176 offset:3072
	ds_read_b128 v[180:183], v177
	ds_read_b128 v[184:187], v177 offset:1024
	ds_read_b128 v[188:191], v177 offset:2048
	ds_read_b128 v[192:195], v177 offset:3072
	s_add_u32 s14, s50, 0xfff00080
	s_addc_u32 s15, s51, -1
	s_cmp_eq_u32 s77, 60
	s_cselect_b32 s55, s35, s15
	s_cselect_b32 s54, s49, s14
	s_cselect_b32 s53, s43, s76
	s_cselect_b32 s52, s74, s75
	v_lshl_add_u64 v[228:229], s[50:51], 0, v[142:143]
	s_add_i32 m0, s61, 0xc000
	ds_read_b128 v[196:199], v178
	ds_read_b128 v[200:203], v178 offset:1024
	ds_read_b128 v[204:207], v178 offset:2048
	ds_read_b128 v[208:211], v178 offset:3072
	ds_read_b128 v[212:215], v178 offset:4096
	ds_read_b128 v[216:219], v178 offset:5120
	ds_read_b128 v[220:223], v178 offset:6144
	ds_read_b128 v[224:227], v178 offset:7168
	global_load_lds_dwordx4 v[228:229], off
	v_lshl_add_u64 v[228:229], s[50:51], 0, v[144:145]
	s_add_i32 m0, s61, 0xe000
	s_nop 0
	global_load_lds_dwordx4 v[228:229], off
	s_waitcnt vmcnt(8)
	s_waitcnt lgkmcnt(0)
	s_setprio 1
	s_barrier
	v_mfma_f32_16x16x32_bf16 v[124:127], v[152:155], v[196:199], v[124:127]
	v_mfma_f32_16x16x32_bf16 v[120:123], v[160:163], v[196:199], v[120:123]
	v_mfma_f32_16x16x32_bf16 v[104:107], v[160:163], v[204:207], v[104:107]
	v_mfma_f32_16x16x32_bf16 v[108:111], v[152:155], v[204:207], v[108:111]
	v_mfma_f32_16x16x32_bf16 v[92:95], v[152:155], v[212:215], v[92:95]
	v_mfma_f32_16x16x32_bf16 v[88:91], v[160:163], v[212:215], v[88:91]
	v_mfma_f32_16x16x32_bf16 v[72:75], v[160:163], v[220:223], v[72:75]
	v_mfma_f32_16x16x32_bf16 v[76:79], v[152:155], v[220:223], v[76:79]
	v_mfma_f32_16x16x32_bf16 v[76:79], v[156:159], v[224:227], v[76:79]
	v_mfma_f32_16x16x32_bf16 v[72:75], v[164:167], v[224:227], v[72:75]
	v_mfma_f32_16x16x32_bf16 v[88:91], v[164:167], v[216:219], v[88:91]
	v_mfma_f32_16x16x32_bf16 v[92:95], v[156:159], v[216:219], v[92:95]
	v_mfma_f32_16x16x32_bf16 v[108:111], v[156:159], v[208:211], v[108:111]
	v_mfma_f32_16x16x32_bf16 v[104:107], v[164:167], v[208:211], v[104:107]
	v_mfma_f32_16x16x32_bf16 v[120:123], v[164:167], v[200:203], v[120:123]
	v_mfma_f32_16x16x32_bf16 v[124:127], v[156:159], v[200:203], v[124:127]
	v_mfma_f32_16x16x32_bf16 v[116:119], v[180:183], v[196:199], v[116:119]
	v_mfma_f32_16x16x32_bf16 v[112:115], v[188:191], v[196:199], v[112:115]
	v_mfma_f32_16x16x32_bf16 v[96:99], v[188:191], v[204:207], v[96:99]
	v_mfma_f32_16x16x32_bf16 v[100:103], v[180:183], v[204:207], v[100:103]
	v_mfma_f32_16x16x32_bf16 v[84:87], v[180:183], v[212:215], v[84:87]
	v_mfma_f32_16x16x32_bf16 v[80:83], v[188:191], v[212:215], v[80:83]
	v_mfma_f32_16x16x32_bf16 v[64:67], v[188:191], v[220:223], v[64:67]
	v_mfma_f32_16x16x32_bf16 v[68:71], v[180:183], v[220:223], v[68:71]
	v_mfma_f32_16x16x32_bf16 v[68:71], v[184:187], v[224:227], v[68:71]
	v_mfma_f32_16x16x32_bf16 v[64:67], v[192:195], v[224:227], v[64:67]
	v_mfma_f32_16x16x32_bf16 v[80:83], v[192:195], v[216:219], v[80:83]
	v_mfma_f32_16x16x32_bf16 v[84:87], v[184:187], v[216:219], v[84:87]
	v_mfma_f32_16x16x32_bf16 v[100:103], v[184:187], v[208:211], v[100:103]
	v_mfma_f32_16x16x32_bf16 v[96:99], v[192:195], v[208:211], v[96:99]
	v_mfma_f32_16x16x32_bf16 v[112:115], v[192:195], v[200:203], v[112:115]
	v_mfma_f32_16x16x32_bf16 v[116:119], v[184:187], v[200:203], v[116:119]
	s_barrier
	s_setprio 0
	s_add_i32 s14, s70, s56
	v_lshl_add_u64 v[228:229], s[52:53], 0, v[132:133]
	s_mov_b32 m0, s14
	ds_read_b128 v[196:199], v178 offset:16384
	ds_read_b128 v[200:203], v178 offset:17408
	ds_read_b128 v[204:207], v178 offset:18432
	ds_read_b128 v[208:211], v178 offset:19456
	ds_read_b128 v[212:215], v178 offset:20480
	ds_read_b128 v[216:219], v178 offset:21504
	ds_read_b128 v[220:223], v178 offset:22528
	ds_read_b128 v[224:227], v178 offset:23552
	global_load_lds_dwordx4 v[228:229], off
	s_add_i32 m0, s14, 0x2000
	s_add_u32 s78, s52, 0x100000
	v_lshl_add_u64 v[230:231], s[52:53], 0, v[128:129]
	s_addc_u32 s79, s53, 0
	s_add_i32 s14, s71, s56
	global_load_lds_dwordx4 v[230:231], off
	v_lshl_add_u64 v[232:233], s[78:79], 0, v[132:133]
	s_mov_b32 m0, s14
	v_lshl_add_u64 v[234:235], s[54:55], 0, v[130:131]
	global_load_lds_dwordx4 v[232:233], off
	v_lshl_add_u64 v[232:233], s[78:79], 0, v[128:129]
	s_add_i32 m0, s14, 0x2000
	s_nop 0
	global_load_lds_dwordx4 v[232:233], off
	v_lshl_add_u64 v[232:233], s[54:55], 0, v[134:135]
	s_mov_b32 m0, s61
	s_nop 0
	global_load_lds_dwordx4 v[232:233], off
	s_mov_b32 m0, s62
	s_nop 0
	global_load_lds_dwordx4 v[234:235], off
	s_waitcnt vmcnt(8)
	s_waitcnt lgkmcnt(0)
	s_setprio 1
	s_barrier
	v_mfma_f32_16x16x32_bf16 v[60:63], v[152:155], v[196:199], v[60:63]
	v_mfma_f32_16x16x32_bf16 v[56:59], v[160:163], v[196:199], v[56:59]
	v_mfma_f32_16x16x32_bf16 v[40:43], v[160:163], v[204:207], v[40:43]
	v_mfma_f32_16x16x32_bf16 v[44:47], v[152:155], v[204:207], v[44:47]
	v_mfma_f32_16x16x32_bf16 v[28:31], v[152:155], v[212:215], v[28:31]
	v_mfma_f32_16x16x32_bf16 v[24:27], v[160:163], v[212:215], v[24:27]
	v_mfma_f32_16x16x32_bf16 v[8:11], v[160:163], v[220:223], v[8:11]
	v_mfma_f32_16x16x32_bf16 v[12:15], v[152:155], v[220:223], v[12:15]
	v_mfma_f32_16x16x32_bf16 v[12:15], v[156:159], v[224:227], v[12:15]
	v_mfma_f32_16x16x32_bf16 v[8:11], v[164:167], v[224:227], v[8:11]
	v_mfma_f32_16x16x32_bf16 v[24:27], v[164:167], v[216:219], v[24:27]
	v_mfma_f32_16x16x32_bf16 v[28:31], v[156:159], v[216:219], v[28:31]
	v_mfma_f32_16x16x32_bf16 v[44:47], v[156:159], v[208:211], v[44:47]
	v_mfma_f32_16x16x32_bf16 v[40:43], v[164:167], v[208:211], v[40:43]
	v_mfma_f32_16x16x32_bf16 v[56:59], v[164:167], v[200:203], v[56:59]
	v_mfma_f32_16x16x32_bf16 v[60:63], v[156:159], v[200:203], v[60:63]
	v_mfma_f32_16x16x32_bf16 v[52:55], v[180:183], v[196:199], v[52:55]
	v_mfma_f32_16x16x32_bf16 v[48:51], v[188:191], v[196:199], v[48:51]
	v_mfma_f32_16x16x32_bf16 v[32:35], v[188:191], v[204:207], v[32:35]
	v_mfma_f32_16x16x32_bf16 v[36:39], v[180:183], v[204:207], v[36:39]
	v_mfma_f32_16x16x32_bf16 v[20:23], v[180:183], v[212:215], v[20:23]
	v_mfma_f32_16x16x32_bf16 v[16:19], v[188:191], v[212:215], v[16:19]
	v_mfma_f32_16x16x32_bf16 v[0:3], v[188:191], v[220:223], v[0:3]
	v_mfma_f32_16x16x32_bf16 v[4:7], v[180:183], v[220:223], v[4:7]
	v_mfma_f32_16x16x32_bf16 v[4:7], v[184:187], v[224:227], v[4:7]
	v_mfma_f32_16x16x32_bf16 v[0:3], v[192:195], v[224:227], v[0:3]
	v_mfma_f32_16x16x32_bf16 v[16:19], v[192:195], v[216:219], v[16:19]
	v_mfma_f32_16x16x32_bf16 v[20:23], v[184:187], v[216:219], v[20:23]
	v_mfma_f32_16x16x32_bf16 v[36:39], v[184:187], v[208:211], v[36:39]
	v_mfma_f32_16x16x32_bf16 v[32:35], v[192:195], v[208:211], v[32:35]
	v_mfma_f32_16x16x32_bf16 v[48:51], v[192:195], v[200:203], v[48:51]
	v_mfma_f32_16x16x32_bf16 v[52:55], v[184:187], v[200:203], v[52:55]
	s_barrier
	s_setprio 0
	s_add_i32 s14, 0, 0x18000
	v_add_u32_e32 v151, s14, v169
	s_add_i32 s15, 0, 0x1c000
	ds_read_b128 v[152:155], v151
	ds_read_b128 v[156:159], v151 offset:1024
	ds_read_b128 v[160:163], v151 offset:2048
	ds_read_b128 v[164:167], v151 offset:3072
	v_add_u32_e32 v151, s15, v169
	ds_read_b128 v[180:183], v151
	ds_read_b128 v[184:187], v151 offset:1024
	ds_read_b128 v[188:191], v151 offset:2048
	ds_read_b128 v[192:195], v151 offset:3072
	s_add_u32 s54, s54, 0x100000
	s_addc_u32 s55, s55, 0
	s_mov_b32 m0, s63
	v_lshl_add_u64 v[236:237], s[54:55], 0, v[134:135]
	ds_read_b128 v[196:199], v178 offset:32768
	ds_read_b128 v[200:203], v178 offset:33792
	ds_read_b128 v[204:207], v178 offset:34816
	ds_read_b128 v[208:211], v178 offset:35840
	ds_read_b128 v[212:215], v178 offset:36864
	ds_read_b128 v[216:219], v178 offset:37888
	ds_read_b128 v[220:223], v178 offset:38912
	ds_read_b128 v[224:227], v178 offset:39936
	global_load_lds_dwordx4 v[236:237], off
	v_lshl_add_u64 v[236:237], s[54:55], 0, v[130:131]
	s_mov_b32 m0, s64
	s_nop 0
	global_load_lds_dwordx4 v[236:237], off
	s_waitcnt vmcnt(8)
	s_waitcnt lgkmcnt(0)
	s_setprio 1
	s_barrier
	v_mfma_f32_16x16x32_bf16 v[124:127], v[152:155], v[196:199], v[124:127]
	v_mfma_f32_16x16x32_bf16 v[120:123], v[160:163], v[196:199], v[120:123]
	v_mfma_f32_16x16x32_bf16 v[104:107], v[160:163], v[204:207], v[104:107]
	v_mfma_f32_16x16x32_bf16 v[108:111], v[152:155], v[204:207], v[108:111]
	v_mfma_f32_16x16x32_bf16 v[92:95], v[152:155], v[212:215], v[92:95]
	v_mfma_f32_16x16x32_bf16 v[88:91], v[160:163], v[212:215], v[88:91]
	v_mfma_f32_16x16x32_bf16 v[72:75], v[160:163], v[220:223], v[72:75]
	v_mfma_f32_16x16x32_bf16 v[76:79], v[152:155], v[220:223], v[76:79]
	v_mfma_f32_16x16x32_bf16 v[76:79], v[156:159], v[224:227], v[76:79]
	v_mfma_f32_16x16x32_bf16 v[72:75], v[164:167], v[224:227], v[72:75]
	v_mfma_f32_16x16x32_bf16 v[88:91], v[164:167], v[216:219], v[88:91]
	v_mfma_f32_16x16x32_bf16 v[92:95], v[156:159], v[216:219], v[92:95]
	v_mfma_f32_16x16x32_bf16 v[108:111], v[156:159], v[208:211], v[108:111]
	v_mfma_f32_16x16x32_bf16 v[104:107], v[164:167], v[208:211], v[104:107]
	v_mfma_f32_16x16x32_bf16 v[120:123], v[164:167], v[200:203], v[120:123]
	v_mfma_f32_16x16x32_bf16 v[124:127], v[156:159], v[200:203], v[124:127]
	v_mfma_f32_16x16x32_bf16 v[116:119], v[180:183], v[196:199], v[116:119]
	v_mfma_f32_16x16x32_bf16 v[112:115], v[188:191], v[196:199], v[112:115]
	v_mfma_f32_16x16x32_bf16 v[96:99], v[188:191], v[204:207], v[96:99]
	v_mfma_f32_16x16x32_bf16 v[100:103], v[180:183], v[204:207], v[100:103]
	v_mfma_f32_16x16x32_bf16 v[84:87], v[180:183], v[212:215], v[84:87]
	v_mfma_f32_16x16x32_bf16 v[80:83], v[188:191], v[212:215], v[80:83]
	v_mfma_f32_16x16x32_bf16 v[64:67], v[188:191], v[220:223], v[64:67]
	v_mfma_f32_16x16x32_bf16 v[68:71], v[180:183], v[220:223], v[68:71]
	v_mfma_f32_16x16x32_bf16 v[68:71], v[184:187], v[224:227], v[68:71]
	v_mfma_f32_16x16x32_bf16 v[64:67], v[192:195], v[224:227], v[64:67]
	v_mfma_f32_16x16x32_bf16 v[80:83], v[192:195], v[216:219], v[80:83]
	v_mfma_f32_16x16x32_bf16 v[84:87], v[184:187], v[216:219], v[84:87]
	v_mfma_f32_16x16x32_bf16 v[100:103], v[184:187], v[208:211], v[100:103]
	v_mfma_f32_16x16x32_bf16 v[96:99], v[192:195], v[208:211], v[96:99]
	v_mfma_f32_16x16x32_bf16 v[112:115], v[192:195], v[200:203], v[112:115]
	v_mfma_f32_16x16x32_bf16 v[116:119], v[184:187], v[200:203], v[116:119]
	s_barrier
	s_setprio 0
	s_add_i32 s14, s14, s56
	v_lshl_add_u64 v[228:229], v[228:229], 0, s[38:39]
	s_mov_b32 m0, s14
	ds_read_b128 v[196:199], v178 offset:49152
	ds_read_b128 v[200:203], v178 offset:50176
	ds_read_b128 v[204:207], v178 offset:51200
	ds_read_b128 v[208:211], v178 offset:52224
	ds_read_b128 v[212:215], v178 offset:53248
	ds_read_b128 v[216:219], v178 offset:54272
	ds_read_b128 v[220:223], v178 offset:55296
	ds_read_b128 v[224:227], v178 offset:56320
	global_load_lds_dwordx4 v[228:229], off
	s_add_i32 m0, s14, 0x2000
	s_add_u32 s52, s52, 0x100080
	v_lshl_add_u64 v[228:229], v[230:231], 0, s[38:39]
	s_addc_u32 s53, s53, 0
	s_add_i32 s14, s15, s56
	global_load_lds_dwordx4 v[228:229], off
	v_lshl_add_u64 v[228:229], s[52:53], 0, v[132:133]
	s_mov_b32 m0, s14
	s_nop 0
	global_load_lds_dwordx4 v[228:229], off
	v_lshl_add_u64 v[228:229], s[52:53], 0, v[128:129]
	s_add_i32 m0, s14, 0x2000
	s_nop 0
	global_load_lds_dwordx4 v[228:229], off
	v_lshl_add_u64 v[228:229], v[232:233], 0, s[38:39]
	s_mov_b32 m0, s65
	s_nop 0
	global_load_lds_dwordx4 v[228:229], off
	v_lshl_add_u64 v[228:229], v[234:235], 0, s[38:39]
	s_mov_b32 m0, s66
	s_nop 0
	global_load_lds_dwordx4 v[228:229], off
	s_waitcnt vmcnt(8)
	s_waitcnt lgkmcnt(0)
	s_setprio 1
	s_barrier
	v_mfma_f32_16x16x32_bf16 v[60:63], v[152:155], v[196:199], v[60:63]
	v_mfma_f32_16x16x32_bf16 v[56:59], v[160:163], v[196:199], v[56:59]
	v_mfma_f32_16x16x32_bf16 v[40:43], v[160:163], v[204:207], v[40:43]
	v_mfma_f32_16x16x32_bf16 v[44:47], v[152:155], v[204:207], v[44:47]
	v_mfma_f32_16x16x32_bf16 v[28:31], v[152:155], v[212:215], v[28:31]
	v_mfma_f32_16x16x32_bf16 v[24:27], v[160:163], v[212:215], v[24:27]
	v_mfma_f32_16x16x32_bf16 v[8:11], v[160:163], v[220:223], v[8:11]
	v_mfma_f32_16x16x32_bf16 v[12:15], v[152:155], v[220:223], v[12:15]
	v_mfma_f32_16x16x32_bf16 v[12:15], v[156:159], v[224:227], v[12:15]
	v_mfma_f32_16x16x32_bf16 v[8:11], v[164:167], v[224:227], v[8:11]
	v_mfma_f32_16x16x32_bf16 v[24:27], v[164:167], v[216:219], v[24:27]
	v_mfma_f32_16x16x32_bf16 v[28:31], v[156:159], v[216:219], v[28:31]
	v_mfma_f32_16x16x32_bf16 v[44:47], v[156:159], v[208:211], v[44:47]
	v_mfma_f32_16x16x32_bf16 v[40:43], v[164:167], v[208:211], v[40:43]
	v_mfma_f32_16x16x32_bf16 v[56:59], v[164:167], v[200:203], v[56:59]
	v_mfma_f32_16x16x32_bf16 v[60:63], v[156:159], v[200:203], v[60:63]
	v_mfma_f32_16x16x32_bf16 v[52:55], v[180:183], v[196:199], v[52:55]
	v_mfma_f32_16x16x32_bf16 v[48:51], v[188:191], v[196:199], v[48:51]
	v_mfma_f32_16x16x32_bf16 v[32:35], v[188:191], v[204:207], v[32:35]
	v_mfma_f32_16x16x32_bf16 v[36:39], v[180:183], v[204:207], v[36:39]
	v_mfma_f32_16x16x32_bf16 v[20:23], v[180:183], v[212:215], v[20:23]
	v_mfma_f32_16x16x32_bf16 v[16:19], v[188:191], v[212:215], v[16:19]
	v_mfma_f32_16x16x32_bf16 v[0:3], v[188:191], v[220:223], v[0:3]
	v_mfma_f32_16x16x32_bf16 v[4:7], v[180:183], v[220:223], v[4:7]
	v_mfma_f32_16x16x32_bf16 v[4:7], v[184:187], v[224:227], v[4:7]
	v_mfma_f32_16x16x32_bf16 v[0:3], v[192:195], v[224:227], v[0:3]
	v_mfma_f32_16x16x32_bf16 v[16:19], v[192:195], v[216:219], v[16:19]
	v_mfma_f32_16x16x32_bf16 v[20:23], v[184:187], v[216:219], v[20:23]
	v_mfma_f32_16x16x32_bf16 v[36:39], v[184:187], v[208:211], v[36:39]
	v_mfma_f32_16x16x32_bf16 v[32:35], v[192:195], v[208:211], v[32:35]
	v_mfma_f32_16x16x32_bf16 v[48:51], v[192:195], v[200:203], v[48:51]
	v_mfma_f32_16x16x32_bf16 v[52:55], v[184:187], v[200:203], v[52:55]
	s_barrier
	s_setprio 0
	s_add_i32 s77, s77, 2
	s_add_u32 s50, s50, 0x100
	s_addc_u32 s51, s51, 0
	s_add_u32 s75, s75, 0x100
	s_addc_u32 s76, s76, 0
	s_cmp_gt_u32 s77, 61
	s_cbranch_scc0 .LBB0_181
	s_and_b64 vcc, exec, s[40:41]
	s_cbranch_vccz .LBB0_184
	s_barrier

.LBB0_751:
	ds_read_b128 v[56:59], v179
	ds_read_b128 v[60:63], v179 offset:1024
	ds_read_b128 v[72:75], v179 offset:2048
	ds_read_b128 v[76:79], v179 offset:3072
	ds_read_b128 v[162:165], v180
	ds_read_b128 v[166:169], v180 offset:1024
	ds_read_b128 v[170:173], v180 offset:2048
	ds_read_b128 v[182:185], v180 offset:3072
	s_add_u32 s14, s62, 0xfff00080
	s_addc_u32 s15, s63, -1
	s_cmp_eq_u32 s79, 60
	s_cselect_b32 s67, s51, s15
	s_cselect_b32 s66, s59, s14
	s_cselect_b32 s65, s53, s78
	s_cselect_b32 s64, s61, s77
	v_lshl_add_u64 v[218:219], s[62:63], 0, v[154:155]
	s_add_i32 m0, s68, 0xc000
	ds_read_b128 v[186:189], v181
	ds_read_b128 v[190:193], v181 offset:1024
	ds_read_b128 v[194:197], v181 offset:2048
	ds_read_b128 v[198:201], v181 offset:3072
	ds_read_b128 v[202:205], v181 offset:4096
	ds_read_b128 v[206:209], v181 offset:5120
	ds_read_b128 v[210:213], v181 offset:6144
	ds_read_b128 v[214:217], v181 offset:7168
	global_load_lds_dwordx4 v[218:219], off
	v_lshl_add_u64 v[218:219], s[62:63], 0, v[156:157]
	s_add_i32 m0, s68, 0xe000
	s_nop 0
	global_load_lds_dwordx4 v[218:219], off
	s_waitcnt vmcnt(8)
	s_waitcnt lgkmcnt(0)
	s_setprio 1
	s_barrier
	v_mfma_f32_16x16x32_bf16 v[140:143], v[56:59], v[186:189], v[140:143]
	v_mfma_f32_16x16x32_bf16 v[136:139], v[72:75], v[186:189], v[136:139]
	v_mfma_f32_16x16x32_bf16 v[120:123], v[72:75], v[194:197], v[120:123]
	v_mfma_f32_16x16x32_bf16 v[124:127], v[56:59], v[194:197], v[124:127]
	v_mfma_f32_16x16x32_bf16 v[108:111], v[56:59], v[202:205], v[108:111]
	v_mfma_f32_16x16x32_bf16 v[104:107], v[72:75], v[202:205], v[104:107]
	v_mfma_f32_16x16x32_bf16 v[88:91], v[72:75], v[210:213], v[88:91]
	v_mfma_f32_16x16x32_bf16 v[92:95], v[56:59], v[210:213], v[92:95]
	v_mfma_f32_16x16x32_bf16 v[92:95], v[60:63], v[214:217], v[92:95]
	v_mfma_f32_16x16x32_bf16 v[88:91], v[76:79], v[214:217], v[88:91]
	v_mfma_f32_16x16x32_bf16 v[104:107], v[76:79], v[206:209], v[104:107]
	v_mfma_f32_16x16x32_bf16 v[108:111], v[60:63], v[206:209], v[108:111]
	v_mfma_f32_16x16x32_bf16 v[124:127], v[60:63], v[198:201], v[124:127]
	v_mfma_f32_16x16x32_bf16 v[120:123], v[76:79], v[198:201], v[120:123]
	v_mfma_f32_16x16x32_bf16 v[136:139], v[76:79], v[190:193], v[136:139]
	v_mfma_f32_16x16x32_bf16 v[140:143], v[60:63], v[190:193], v[140:143]
	v_mfma_f32_16x16x32_bf16 v[132:135], v[162:165], v[186:189], v[132:135]
	v_mfma_f32_16x16x32_bf16 v[128:131], v[170:173], v[186:189], v[128:131]
	v_mfma_f32_16x16x32_bf16 v[112:115], v[170:173], v[194:197], v[112:115]
	v_mfma_f32_16x16x32_bf16 v[116:119], v[162:165], v[194:197], v[116:119]
	v_mfma_f32_16x16x32_bf16 v[100:103], v[162:165], v[202:205], v[100:103]
	v_mfma_f32_16x16x32_bf16 v[96:99], v[170:173], v[202:205], v[96:99]
	v_mfma_f32_16x16x32_bf16 v[80:83], v[170:173], v[210:213], v[80:83]
	v_mfma_f32_16x16x32_bf16 v[84:87], v[162:165], v[210:213], v[84:87]
	v_mfma_f32_16x16x32_bf16 v[84:87], v[166:169], v[214:217], v[84:87]
	v_mfma_f32_16x16x32_bf16 v[80:83], v[182:185], v[214:217], v[80:83]
	v_mfma_f32_16x16x32_bf16 v[96:99], v[182:185], v[206:209], v[96:99]
	v_mfma_f32_16x16x32_bf16 v[100:103], v[166:169], v[206:209], v[100:103]
	v_mfma_f32_16x16x32_bf16 v[116:119], v[166:169], v[198:201], v[116:119]
	v_mfma_f32_16x16x32_bf16 v[112:115], v[182:185], v[198:201], v[112:115]
	v_mfma_f32_16x16x32_bf16 v[128:131], v[182:185], v[190:193], v[128:131]
	v_mfma_f32_16x16x32_bf16 v[132:135], v[166:169], v[190:193], v[132:135]
	s_barrier
	s_setprio 0
	s_add_i32 s14, s75, s49
	v_lshl_add_u64 v[218:219], s[64:65], 0, v[146:147]
	s_mov_b32 m0, s14
	ds_read_b128 v[186:189], v181 offset:16384
	ds_read_b128 v[190:193], v181 offset:17408
	ds_read_b128 v[194:197], v181 offset:18432
	ds_read_b128 v[198:201], v181 offset:19456
	ds_read_b128 v[202:205], v181 offset:20480
	ds_read_b128 v[206:209], v181 offset:21504
	ds_read_b128 v[210:213], v181 offset:22528
	ds_read_b128 v[214:217], v181 offset:23552
	global_load_lds_dwordx4 v[218:219], off
	s_add_i32 m0, s14, 0x2000
	s_add_u32 s14, s64, 0x100000
	v_lshl_add_u64 v[220:221], s[64:65], 0, v[150:151]
	s_addc_u32 s15, s65, 0
	s_add_i32 s80, s76, s49
	global_load_lds_dwordx4 v[220:221], off
	v_lshl_add_u64 v[222:223], s[14:15], 0, v[146:147]
	s_mov_b32 m0, s80
	v_lshl_add_u64 v[224:225], s[66:67], 0, v[148:149]
	global_load_lds_dwordx4 v[222:223], off
	v_lshl_add_u64 v[222:223], s[14:15], 0, v[150:151]
	s_add_i32 m0, s80, 0x2000
	s_nop 0
	global_load_lds_dwordx4 v[222:223], off
	v_lshl_add_u64 v[222:223], s[66:67], 0, v[144:145]
	s_mov_b32 m0, s68
	s_nop 0
	global_load_lds_dwordx4 v[222:223], off
	s_mov_b32 m0, s69
	s_nop 0
	global_load_lds_dwordx4 v[224:225], off
	s_waitcnt vmcnt(8)
	s_waitcnt lgkmcnt(0)
	s_setprio 1
	s_barrier
	v_mfma_f32_16x16x32_bf16 v[68:71], v[56:59], v[186:189], v[68:71]
	v_mfma_f32_16x16x32_bf16 v[64:67], v[72:75], v[186:189], v[64:67]
	v_mfma_f32_16x16x32_bf16 v[40:43], v[72:75], v[194:197], v[40:43]
	v_mfma_f32_16x16x32_bf16 v[44:47], v[56:59], v[194:197], v[44:47]
	v_mfma_f32_16x16x32_bf16 v[28:31], v[56:59], v[202:205], v[28:31]
	v_mfma_f32_16x16x32_bf16 v[24:27], v[72:75], v[202:205], v[24:27]
	v_mfma_f32_16x16x32_bf16 v[8:11], v[72:75], v[210:213], v[8:11]
	v_mfma_f32_16x16x32_bf16 v[12:15], v[56:59], v[210:213], v[12:15]
	v_mfma_f32_16x16x32_bf16 v[12:15], v[60:63], v[214:217], v[12:15]
	v_mfma_f32_16x16x32_bf16 v[8:11], v[76:79], v[214:217], v[8:11]
	v_mfma_f32_16x16x32_bf16 v[24:27], v[76:79], v[206:209], v[24:27]
	v_mfma_f32_16x16x32_bf16 v[28:31], v[60:63], v[206:209], v[28:31]
	v_mfma_f32_16x16x32_bf16 v[44:47], v[60:63], v[198:201], v[44:47]
	v_mfma_f32_16x16x32_bf16 v[40:43], v[76:79], v[198:201], v[40:43]
	v_mfma_f32_16x16x32_bf16 v[64:67], v[76:79], v[190:193], v[64:67]
	v_mfma_f32_16x16x32_bf16 v[68:71], v[60:63], v[190:193], v[68:71]
	v_mfma_f32_16x16x32_bf16 v[52:55], v[162:165], v[186:189], v[52:55]
	v_mfma_f32_16x16x32_bf16 v[48:51], v[170:173], v[186:189], v[48:51]
	v_mfma_f32_16x16x32_bf16 v[32:35], v[170:173], v[194:197], v[32:35]
	v_mfma_f32_16x16x32_bf16 v[36:39], v[162:165], v[194:197], v[36:39]
	v_mfma_f32_16x16x32_bf16 v[20:23], v[162:165], v[202:205], v[20:23]
	v_mfma_f32_16x16x32_bf16 v[16:19], v[170:173], v[202:205], v[16:19]
	v_mfma_f32_16x16x32_bf16 v[0:3], v[170:173], v[210:213], v[0:3]
	v_mfma_f32_16x16x32_bf16 v[4:7], v[162:165], v[210:213], v[4:7]
	v_mfma_f32_16x16x32_bf16 v[4:7], v[166:169], v[214:217], v[4:7]
	v_mfma_f32_16x16x32_bf16 v[0:3], v[182:185], v[214:217], v[0:3]
	v_mfma_f32_16x16x32_bf16 v[16:19], v[182:185], v[206:209], v[16:19]
	v_mfma_f32_16x16x32_bf16 v[20:23], v[166:169], v[206:209], v[20:23]
	v_mfma_f32_16x16x32_bf16 v[36:39], v[166:169], v[198:201], v[36:39]
	v_mfma_f32_16x16x32_bf16 v[32:35], v[182:185], v[198:201], v[32:35]
	v_mfma_f32_16x16x32_bf16 v[48:51], v[182:185], v[190:193], v[48:51]
	v_mfma_f32_16x16x32_bf16 v[52:55], v[166:169], v[190:193], v[52:55]
	s_barrier
	s_setprio 0
	s_add_i32 s80, 0, 0x18000
	s_add_i32 s81, 0, 0x1c000
	v_add_u32_e32 v76, s80, v175
	v_add_u32_e32 v153, s81, v175
	ds_read_b128 v[56:59], v76
	ds_read_b128 v[60:63], v76 offset:1024
	ds_read_b128 v[72:75], v76 offset:2048
	ds_read_b128 v[76:79], v76 offset:3072
	ds_read_b128 v[162:165], v153
	ds_read_b128 v[166:169], v153 offset:1024
	ds_read_b128 v[170:173], v153 offset:2048
	ds_read_b128 v[182:185], v153 offset:3072
	s_add_u32 s14, s66, 0x100000
	s_addc_u32 s15, s67, 0
	s_mov_b32 m0, s70
	v_lshl_add_u64 v[226:227], s[14:15], 0, v[144:145]
	ds_read_b128 v[186:189], v181 offset:32768
	ds_read_b128 v[190:193], v181 offset:33792
	ds_read_b128 v[194:197], v181 offset:34816
	ds_read_b128 v[198:201], v181 offset:35840
	ds_read_b128 v[202:205], v181 offset:36864
	ds_read_b128 v[206:209], v181 offset:37888
	ds_read_b128 v[210:213], v181 offset:38912
	ds_read_b128 v[214:217], v181 offset:39936
	global_load_lds_dwordx4 v[226:227], off
	v_lshl_add_u64 v[226:227], s[14:15], 0, v[148:149]
	s_mov_b32 m0, s71
	s_nop 0
	global_load_lds_dwordx4 v[226:227], off
	s_waitcnt vmcnt(8)
	s_waitcnt lgkmcnt(0)
	s_setprio 1
	s_barrier
	v_mfma_f32_16x16x32_bf16 v[140:143], v[56:59], v[186:189], v[140:143]
	v_mfma_f32_16x16x32_bf16 v[136:139], v[72:75], v[186:189], v[136:139]
	v_mfma_f32_16x16x32_bf16 v[120:123], v[72:75], v[194:197], v[120:123]
	v_mfma_f32_16x16x32_bf16 v[124:127], v[56:59], v[194:197], v[124:127]
	v_mfma_f32_16x16x32_bf16 v[108:111], v[56:59], v[202:205], v[108:111]
	v_mfma_f32_16x16x32_bf16 v[104:107], v[72:75], v[202:205], v[104:107]
	v_mfma_f32_16x16x32_bf16 v[88:91], v[72:75], v[210:213], v[88:91]
	v_mfma_f32_16x16x32_bf16 v[92:95], v[56:59], v[210:213], v[92:95]
	v_mfma_f32_16x16x32_bf16 v[92:95], v[60:63], v[214:217], v[92:95]
	v_mfma_f32_16x16x32_bf16 v[88:91], v[76:79], v[214:217], v[88:91]
	v_mfma_f32_16x16x32_bf16 v[104:107], v[76:79], v[206:209], v[104:107]
	v_mfma_f32_16x16x32_bf16 v[108:111], v[60:63], v[206:209], v[108:111]
	v_mfma_f32_16x16x32_bf16 v[124:127], v[60:63], v[198:201], v[124:127]
	v_mfma_f32_16x16x32_bf16 v[120:123], v[76:79], v[198:201], v[120:123]
	v_mfma_f32_16x16x32_bf16 v[136:139], v[76:79], v[190:193], v[136:139]
	v_mfma_f32_16x16x32_bf16 v[140:143], v[60:63], v[190:193], v[140:143]
	v_mfma_f32_16x16x32_bf16 v[132:135], v[162:165], v[186:189], v[132:135]
	v_mfma_f32_16x16x32_bf16 v[128:131], v[170:173], v[186:189], v[128:131]
	v_mfma_f32_16x16x32_bf16 v[112:115], v[170:173], v[194:197], v[112:115]
	v_mfma_f32_16x16x32_bf16 v[116:119], v[162:165], v[194:197], v[116:119]
	v_mfma_f32_16x16x32_bf16 v[100:103], v[162:165], v[202:205], v[100:103]
	v_mfma_f32_16x16x32_bf16 v[96:99], v[170:173], v[202:205], v[96:99]
	v_mfma_f32_16x16x32_bf16 v[80:83], v[170:173], v[210:213], v[80:83]
	v_mfma_f32_16x16x32_bf16 v[84:87], v[162:165], v[210:213], v[84:87]
	v_mfma_f32_16x16x32_bf16 v[84:87], v[166:169], v[214:217], v[84:87]
	v_mfma_f32_16x16x32_bf16 v[80:83], v[182:185], v[214:217], v[80:83]
	v_mfma_f32_16x16x32_bf16 v[96:99], v[182:185], v[206:209], v[96:99]
	v_mfma_f32_16x16x32_bf16 v[100:103], v[166:169], v[206:209], v[100:103]
	v_mfma_f32_16x16x32_bf16 v[116:119], v[166:169], v[198:201], v[116:119]
	v_mfma_f32_16x16x32_bf16 v[112:115], v[182:185], v[198:201], v[112:115]
	v_mfma_f32_16x16x32_bf16 v[128:131], v[182:185], v[190:193], v[128:131]
	v_mfma_f32_16x16x32_bf16 v[132:135], v[166:169], v[190:193], v[132:135]
	s_barrier
	s_setprio 0
	s_add_i32 s14, s80, s49
	v_lshl_add_u64 v[218:219], v[218:219], 0, s[44:45]
	s_mov_b32 m0, s14
	ds_read_b128 v[186:189], v181 offset:49152
	ds_read_b128 v[190:193], v181 offset:50176
	ds_read_b128 v[194:197], v181 offset:51200
	ds_read_b128 v[198:201], v181 offset:52224
	ds_read_b128 v[202:205], v181 offset:53248
	ds_read_b128 v[206:209], v181 offset:54272
	ds_read_b128 v[210:213], v181 offset:55296
	ds_read_b128 v[214:217], v181 offset:56320
	global_load_lds_dwordx4 v[218:219], off
	s_add_i32 m0, s14, 0x2000
	s_add_u32 s14, s64, 0x100080
	v_lshl_add_u64 v[218:219], v[220:221], 0, s[44:45]
	s_addc_u32 s15, s65, 0
	s_add_i32 s64, s81, s49
	global_load_lds_dwordx4 v[218:219], off
	v_lshl_add_u64 v[218:219], s[14:15], 0, v[146:147]
	s_mov_b32 m0, s64
	s_nop 0
	global_load_lds_dwordx4 v[218:219], off
	v_lshl_add_u64 v[218:219], s[14:15], 0, v[150:151]
	s_add_i32 m0, s64, 0x2000
	s_nop 0
	global_load_lds_dwordx4 v[218:219], off
	v_lshl_add_u64 v[218:219], v[222:223], 0, s[44:45]
	s_mov_b32 m0, s72
	s_nop 0
	global_load_lds_dwordx4 v[218:219], off
	v_lshl_add_u64 v[218:219], v[224:225], 0, s[44:45]
	s_mov_b32 m0, s73
	s_nop 0
	global_load_lds_dwordx4 v[218:219], off
	s_waitcnt vmcnt(8)
	s_waitcnt lgkmcnt(0)
	s_setprio 1
	s_barrier
	v_mfma_f32_16x16x32_bf16 v[68:71], v[56:59], v[186:189], v[68:71]
	v_mfma_f32_16x16x32_bf16 v[64:67], v[72:75], v[186:189], v[64:67]
	v_mfma_f32_16x16x32_bf16 v[40:43], v[72:75], v[194:197], v[40:43]
	v_mfma_f32_16x16x32_bf16 v[44:47], v[56:59], v[194:197], v[44:47]
	v_mfma_f32_16x16x32_bf16 v[28:31], v[56:59], v[202:205], v[28:31]
	v_mfma_f32_16x16x32_bf16 v[24:27], v[72:75], v[202:205], v[24:27]
	v_mfma_f32_16x16x32_bf16 v[8:11], v[72:75], v[210:213], v[8:11]
	v_mfma_f32_16x16x32_bf16 v[12:15], v[56:59], v[210:213], v[12:15]
	v_mfma_f32_16x16x32_bf16 v[12:15], v[60:63], v[214:217], v[12:15]
	v_mfma_f32_16x16x32_bf16 v[8:11], v[76:79], v[214:217], v[8:11]
	v_mfma_f32_16x16x32_bf16 v[24:27], v[76:79], v[206:209], v[24:27]
	v_mfma_f32_16x16x32_bf16 v[28:31], v[60:63], v[206:209], v[28:31]
	v_mfma_f32_16x16x32_bf16 v[44:47], v[60:63], v[198:201], v[44:47]
	v_mfma_f32_16x16x32_bf16 v[40:43], v[76:79], v[198:201], v[40:43]
	v_mfma_f32_16x16x32_bf16 v[64:67], v[76:79], v[190:193], v[64:67]
	v_mfma_f32_16x16x32_bf16 v[68:71], v[60:63], v[190:193], v[68:71]
	v_mfma_f32_16x16x32_bf16 v[52:55], v[162:165], v[186:189], v[52:55]
	v_mfma_f32_16x16x32_bf16 v[48:51], v[170:173], v[186:189], v[48:51]
	v_mfma_f32_16x16x32_bf16 v[32:35], v[170:173], v[194:197], v[32:35]
	v_mfma_f32_16x16x32_bf16 v[36:39], v[162:165], v[194:197], v[36:39]
	v_mfma_f32_16x16x32_bf16 v[20:23], v[162:165], v[202:205], v[20:23]
	v_mfma_f32_16x16x32_bf16 v[16:19], v[170:173], v[202:205], v[16:19]
	v_mfma_f32_16x16x32_bf16 v[0:3], v[170:173], v[210:213], v[0:3]
	v_mfma_f32_16x16x32_bf16 v[4:7], v[162:165], v[210:213], v[4:7]
	v_mfma_f32_16x16x32_bf16 v[4:7], v[166:169], v[214:217], v[4:7]
	v_mfma_f32_16x16x32_bf16 v[0:3], v[182:185], v[214:217], v[0:3]
	v_mfma_f32_16x16x32_bf16 v[16:19], v[182:185], v[206:209], v[16:19]
	v_mfma_f32_16x16x32_bf16 v[20:23], v[166:169], v[206:209], v[20:23]
	v_mfma_f32_16x16x32_bf16 v[36:39], v[166:169], v[198:201], v[36:39]
	v_mfma_f32_16x16x32_bf16 v[32:35], v[182:185], v[198:201], v[32:35]
	v_mfma_f32_16x16x32_bf16 v[48:51], v[182:185], v[190:193], v[48:51]
	v_mfma_f32_16x16x32_bf16 v[52:55], v[166:169], v[190:193], v[52:55]
	s_barrier
	s_setprio 0
	s_add_i32 s79, s79, 2
	s_add_u32 s62, s62, 0x100
	s_addc_u32 s63, s63, 0
	s_add_u32 s77, s77, 0x100
	s_addc_u32 s78, s78, 0
	s_cmp_gt_u32 s79, 61
	s_cbranch_scc0 .LBB0_751
	s_and_b64 vcc, exec, s[46:47]
	s_cbranch_vccz .LBB0_754
	s_barrier

.LBB0_840:
	ds_read_b128 v[128:131], v183
	ds_read_b128 v[132:135], v183 offset:1024
	ds_read_b128 v[136:139], v183 offset:2048
	ds_read_b128 v[140:143], v183 offset:3072
	ds_read_b128 v[144:147], v184
	ds_read_b128 v[148:151], v184 offset:1024
	ds_read_b128 v[152:155], v184 offset:2048
	ds_read_b128 v[156:159], v184 offset:3072
	s_add_u32 s14, s54, 0xfff00080
	s_addc_u32 s15, s55, -1
	s_cmp_eq_u32 s78, 60
	s_cselect_b32 s59, s45, s15
	s_cselect_b32 s58, s74, s14
	s_cselect_b32 s57, s47, s77
	s_cselect_b32 s56, s75, s76
	v_lshl_add_u64 v[216:217], s[54:55], 0, v[168:169]
	s_add_i32 m0, s53, 0xc000
	ds_read_b128 v[176:179], v185
	ds_read_b128 v[188:191], v185 offset:1024
	ds_read_b128 v[192:195], v185 offset:2048
	ds_read_b128 v[196:199], v185 offset:3072
	ds_read_b128 v[200:203], v185 offset:4096
	ds_read_b128 v[204:207], v185 offset:5120
	ds_read_b128 v[208:211], v185 offset:6144
	ds_read_b128 v[212:215], v185 offset:7168
	global_load_lds_dwordx4 v[216:217], off
	v_lshl_add_u64 v[216:217], s[54:55], 0, v[170:171]
	s_add_i32 m0, s53, 0xe000
	s_nop 0
	global_load_lds_dwordx4 v[216:217], off
	s_waitcnt vmcnt(8)
	s_waitcnt lgkmcnt(0)
	s_setprio 1
	s_barrier
	v_mfma_f32_16x16x32_bf16 v[124:127], v[128:131], v[176:179], v[124:127]
	v_mfma_f32_16x16x32_bf16 v[120:123], v[136:139], v[176:179], v[120:123]
	v_mfma_f32_16x16x32_bf16 v[104:107], v[136:139], v[192:195], v[104:107]
	v_mfma_f32_16x16x32_bf16 v[108:111], v[128:131], v[192:195], v[108:111]
	v_mfma_f32_16x16x32_bf16 v[92:95], v[128:131], v[200:203], v[92:95]
	v_mfma_f32_16x16x32_bf16 v[88:91], v[136:139], v[200:203], v[88:91]
	v_mfma_f32_16x16x32_bf16 v[72:75], v[136:139], v[208:211], v[72:75]
	v_mfma_f32_16x16x32_bf16 v[76:79], v[128:131], v[208:211], v[76:79]
	v_mfma_f32_16x16x32_bf16 v[76:79], v[132:135], v[212:215], v[76:79]
	v_mfma_f32_16x16x32_bf16 v[72:75], v[140:143], v[212:215], v[72:75]
	v_mfma_f32_16x16x32_bf16 v[88:91], v[140:143], v[204:207], v[88:91]
	v_mfma_f32_16x16x32_bf16 v[92:95], v[132:135], v[204:207], v[92:95]
	v_mfma_f32_16x16x32_bf16 v[108:111], v[132:135], v[196:199], v[108:111]
	v_mfma_f32_16x16x32_bf16 v[104:107], v[140:143], v[196:199], v[104:107]
	v_mfma_f32_16x16x32_bf16 v[120:123], v[140:143], v[188:191], v[120:123]
	v_mfma_f32_16x16x32_bf16 v[124:127], v[132:135], v[188:191], v[124:127]
	v_mfma_f32_16x16x32_bf16 v[116:119], v[144:147], v[176:179], v[116:119]
	v_mfma_f32_16x16x32_bf16 v[112:115], v[152:155], v[176:179], v[112:115]
	v_mfma_f32_16x16x32_bf16 v[96:99], v[152:155], v[192:195], v[96:99]
	v_mfma_f32_16x16x32_bf16 v[100:103], v[144:147], v[192:195], v[100:103]
	v_mfma_f32_16x16x32_bf16 v[84:87], v[144:147], v[200:203], v[84:87]
	v_mfma_f32_16x16x32_bf16 v[80:83], v[152:155], v[200:203], v[80:83]
	v_mfma_f32_16x16x32_bf16 v[64:67], v[152:155], v[208:211], v[64:67]
	v_mfma_f32_16x16x32_bf16 v[68:71], v[144:147], v[208:211], v[68:71]
	v_mfma_f32_16x16x32_bf16 v[68:71], v[148:151], v[212:215], v[68:71]
	v_mfma_f32_16x16x32_bf16 v[64:67], v[156:159], v[212:215], v[64:67]
	v_mfma_f32_16x16x32_bf16 v[80:83], v[156:159], v[204:207], v[80:83]
	v_mfma_f32_16x16x32_bf16 v[84:87], v[148:151], v[204:207], v[84:87]
	v_mfma_f32_16x16x32_bf16 v[100:103], v[148:151], v[196:199], v[100:103]
	v_mfma_f32_16x16x32_bf16 v[96:99], v[156:159], v[196:199], v[96:99]
	v_mfma_f32_16x16x32_bf16 v[112:115], v[156:159], v[188:191], v[112:115]
	v_mfma_f32_16x16x32_bf16 v[116:119], v[148:151], v[188:191], v[116:119]
	s_barrier
	s_setprio 0
	s_add_i32 s14, s67, s61
	v_lshl_add_u64 v[216:217], s[56:57], 0, v[162:163]
	s_mov_b32 m0, s14
	ds_read_b128 v[176:179], v185 offset:16384
	ds_read_b128 v[188:191], v185 offset:17408
	ds_read_b128 v[192:195], v185 offset:18432
	ds_read_b128 v[196:199], v185 offset:19456
	ds_read_b128 v[200:203], v185 offset:20480
	ds_read_b128 v[204:207], v185 offset:21504
	ds_read_b128 v[208:211], v185 offset:22528
	ds_read_b128 v[212:215], v185 offset:23552
	global_load_lds_dwordx4 v[216:217], off
	s_add_i32 m0, s14, 0x2000
	s_add_u32 s14, s56, 0x100000
	v_lshl_add_u64 v[218:219], s[56:57], 0, v[166:167]
	s_addc_u32 s15, s57, 0
	s_add_i32 s79, s68, s61
	global_load_lds_dwordx4 v[218:219], off
	v_lshl_add_u64 v[220:221], s[14:15], 0, v[162:163]
	s_mov_b32 m0, s79
	v_lshl_add_u64 v[222:223], s[58:59], 0, v[164:165]
	global_load_lds_dwordx4 v[220:221], off
	v_lshl_add_u64 v[220:221], s[14:15], 0, v[166:167]
	s_add_i32 m0, s79, 0x2000
	s_nop 0
	global_load_lds_dwordx4 v[220:221], off
	v_lshl_add_u64 v[220:221], s[58:59], 0, v[160:161]
	s_mov_b32 m0, s53
	s_nop 0
	global_load_lds_dwordx4 v[220:221], off
	s_mov_b32 m0, s62
	s_nop 0
	global_load_lds_dwordx4 v[222:223], off
	s_waitcnt vmcnt(8)
	s_waitcnt lgkmcnt(0)
	s_setprio 1
	s_barrier
	v_mfma_f32_16x16x32_bf16 v[60:63], v[128:131], v[176:179], v[60:63]
	v_mfma_f32_16x16x32_bf16 v[56:59], v[136:139], v[176:179], v[56:59]
	v_mfma_f32_16x16x32_bf16 v[40:43], v[136:139], v[192:195], v[40:43]
	v_mfma_f32_16x16x32_bf16 v[44:47], v[128:131], v[192:195], v[44:47]
	v_mfma_f32_16x16x32_bf16 v[28:31], v[128:131], v[200:203], v[28:31]
	v_mfma_f32_16x16x32_bf16 v[24:27], v[136:139], v[200:203], v[24:27]
	v_mfma_f32_16x16x32_bf16 v[8:11], v[136:139], v[208:211], v[8:11]
	v_mfma_f32_16x16x32_bf16 v[12:15], v[128:131], v[208:211], v[12:15]
	v_mfma_f32_16x16x32_bf16 v[12:15], v[132:135], v[212:215], v[12:15]
	v_mfma_f32_16x16x32_bf16 v[8:11], v[140:143], v[212:215], v[8:11]
	v_mfma_f32_16x16x32_bf16 v[24:27], v[140:143], v[204:207], v[24:27]
	v_mfma_f32_16x16x32_bf16 v[28:31], v[132:135], v[204:207], v[28:31]
	v_mfma_f32_16x16x32_bf16 v[44:47], v[132:135], v[196:199], v[44:47]
	v_mfma_f32_16x16x32_bf16 v[40:43], v[140:143], v[196:199], v[40:43]
	v_mfma_f32_16x16x32_bf16 v[56:59], v[140:143], v[188:191], v[56:59]
	v_mfma_f32_16x16x32_bf16 v[60:63], v[132:135], v[188:191], v[60:63]
	v_mfma_f32_16x16x32_bf16 v[52:55], v[144:147], v[176:179], v[52:55]
	v_mfma_f32_16x16x32_bf16 v[48:51], v[152:155], v[176:179], v[48:51]
	v_mfma_f32_16x16x32_bf16 v[32:35], v[152:155], v[192:195], v[32:35]
	v_mfma_f32_16x16x32_bf16 v[36:39], v[144:147], v[192:195], v[36:39]
	v_mfma_f32_16x16x32_bf16 v[20:23], v[144:147], v[200:203], v[20:23]
	v_mfma_f32_16x16x32_bf16 v[16:19], v[152:155], v[200:203], v[16:19]
	v_mfma_f32_16x16x32_bf16 v[0:3], v[152:155], v[208:211], v[0:3]
	v_mfma_f32_16x16x32_bf16 v[4:7], v[144:147], v[208:211], v[4:7]
	v_mfma_f32_16x16x32_bf16 v[4:7], v[148:151], v[212:215], v[4:7]
	v_mfma_f32_16x16x32_bf16 v[0:3], v[156:159], v[212:215], v[0:3]
	v_mfma_f32_16x16x32_bf16 v[16:19], v[156:159], v[204:207], v[16:19]
	v_mfma_f32_16x16x32_bf16 v[20:23], v[148:151], v[204:207], v[20:23]
	v_mfma_f32_16x16x32_bf16 v[36:39], v[148:151], v[196:199], v[36:39]
	v_mfma_f32_16x16x32_bf16 v[32:35], v[156:159], v[196:199], v[32:35]
	v_mfma_f32_16x16x32_bf16 v[48:51], v[156:159], v[188:191], v[48:51]
	v_mfma_f32_16x16x32_bf16 v[52:55], v[148:151], v[188:191], v[52:55]
	s_barrier
	s_setprio 0
	s_add_i32 s79, 0, 0x18000
	s_add_i32 s80, 0, 0x1c000
	v_add_u32_e32 v140, s79, v181
	v_add_u32_e32 v156, s80, v181
	ds_read_b128 v[128:131], v140
	ds_read_b128 v[132:135], v140 offset:1024
	ds_read_b128 v[136:139], v140 offset:2048
	ds_read_b128 v[140:143], v140 offset:3072
	ds_read_b128 v[144:147], v156
	ds_read_b128 v[148:151], v156 offset:1024
	ds_read_b128 v[152:155], v156 offset:2048
	ds_read_b128 v[156:159], v156 offset:3072
	s_add_u32 s14, s58, 0x100000
	s_addc_u32 s15, s59, 0
	s_mov_b32 m0, s63
	v_lshl_add_u64 v[224:225], s[14:15], 0, v[160:161]
	ds_read_b128 v[176:179], v185 offset:32768
	ds_read_b128 v[188:191], v185 offset:33792
	ds_read_b128 v[192:195], v185 offset:34816
	ds_read_b128 v[196:199], v185 offset:35840
	ds_read_b128 v[200:203], v185 offset:36864
	ds_read_b128 v[204:207], v185 offset:37888
	ds_read_b128 v[208:211], v185 offset:38912
	ds_read_b128 v[212:215], v185 offset:39936
	global_load_lds_dwordx4 v[224:225], off
	v_lshl_add_u64 v[224:225], s[14:15], 0, v[164:165]
	s_mov_b32 m0, s64
	s_nop 0
	global_load_lds_dwordx4 v[224:225], off
	s_waitcnt vmcnt(8)
	s_waitcnt lgkmcnt(0)
	s_setprio 1
	s_barrier
	v_mfma_f32_16x16x32_bf16 v[124:127], v[128:131], v[176:179], v[124:127]
	v_mfma_f32_16x16x32_bf16 v[120:123], v[136:139], v[176:179], v[120:123]
	v_mfma_f32_16x16x32_bf16 v[104:107], v[136:139], v[192:195], v[104:107]
	v_mfma_f32_16x16x32_bf16 v[108:111], v[128:131], v[192:195], v[108:111]
	v_mfma_f32_16x16x32_bf16 v[92:95], v[128:131], v[200:203], v[92:95]
	v_mfma_f32_16x16x32_bf16 v[88:91], v[136:139], v[200:203], v[88:91]
	v_mfma_f32_16x16x32_bf16 v[72:75], v[136:139], v[208:211], v[72:75]
	v_mfma_f32_16x16x32_bf16 v[76:79], v[128:131], v[208:211], v[76:79]
	v_mfma_f32_16x16x32_bf16 v[76:79], v[132:135], v[212:215], v[76:79]
	v_mfma_f32_16x16x32_bf16 v[72:75], v[140:143], v[212:215], v[72:75]
	v_mfma_f32_16x16x32_bf16 v[88:91], v[140:143], v[204:207], v[88:91]
	v_mfma_f32_16x16x32_bf16 v[92:95], v[132:135], v[204:207], v[92:95]
	v_mfma_f32_16x16x32_bf16 v[108:111], v[132:135], v[196:199], v[108:111]
	v_mfma_f32_16x16x32_bf16 v[104:107], v[140:143], v[196:199], v[104:107]
	v_mfma_f32_16x16x32_bf16 v[120:123], v[140:143], v[188:191], v[120:123]
	v_mfma_f32_16x16x32_bf16 v[124:127], v[132:135], v[188:191], v[124:127]
	v_mfma_f32_16x16x32_bf16 v[116:119], v[144:147], v[176:179], v[116:119]
	v_mfma_f32_16x16x32_bf16 v[112:115], v[152:155], v[176:179], v[112:115]
	v_mfma_f32_16x16x32_bf16 v[96:99], v[152:155], v[192:195], v[96:99]
	v_mfma_f32_16x16x32_bf16 v[100:103], v[144:147], v[192:195], v[100:103]
	v_mfma_f32_16x16x32_bf16 v[84:87], v[144:147], v[200:203], v[84:87]
	v_mfma_f32_16x16x32_bf16 v[80:83], v[152:155], v[200:203], v[80:83]
	v_mfma_f32_16x16x32_bf16 v[64:67], v[152:155], v[208:211], v[64:67]
	v_mfma_f32_16x16x32_bf16 v[68:71], v[144:147], v[208:211], v[68:71]
	v_mfma_f32_16x16x32_bf16 v[68:71], v[148:151], v[212:215], v[68:71]
	v_mfma_f32_16x16x32_bf16 v[64:67], v[156:159], v[212:215], v[64:67]
	v_mfma_f32_16x16x32_bf16 v[80:83], v[156:159], v[204:207], v[80:83]
	v_mfma_f32_16x16x32_bf16 v[84:87], v[148:151], v[204:207], v[84:87]
	v_mfma_f32_16x16x32_bf16 v[100:103], v[148:151], v[196:199], v[100:103]
	v_mfma_f32_16x16x32_bf16 v[96:99], v[156:159], v[196:199], v[96:99]
	v_mfma_f32_16x16x32_bf16 v[112:115], v[156:159], v[188:191], v[112:115]
	v_mfma_f32_16x16x32_bf16 v[116:119], v[148:151], v[188:191], v[116:119]
	s_barrier
	s_setprio 0
	s_add_i32 s14, s79, s61
	v_lshl_add_u64 v[216:217], v[216:217], 0, s[30:31]
	s_mov_b32 m0, s14
	ds_read_b128 v[176:179], v185 offset:49152
	ds_read_b128 v[188:191], v185 offset:50176
	ds_read_b128 v[192:195], v185 offset:51200
	ds_read_b128 v[196:199], v185 offset:52224
	ds_read_b128 v[200:203], v185 offset:53248
	ds_read_b128 v[204:207], v185 offset:54272
	ds_read_b128 v[208:211], v185 offset:55296
	ds_read_b128 v[212:215], v185 offset:56320
	global_load_lds_dwordx4 v[216:217], off
	s_add_i32 m0, s14, 0x2000
	s_add_u32 s14, s56, 0x100080
	v_lshl_add_u64 v[216:217], v[218:219], 0, s[30:31]
	s_addc_u32 s15, s57, 0
	s_add_i32 s56, s80, s61
	global_load_lds_dwordx4 v[216:217], off
	v_lshl_add_u64 v[216:217], s[14:15], 0, v[162:163]
	s_mov_b32 m0, s56
	s_nop 0
	global_load_lds_dwordx4 v[216:217], off
	v_lshl_add_u64 v[216:217], s[14:15], 0, v[166:167]
	s_add_i32 m0, s56, 0x2000
	s_nop 0
	global_load_lds_dwordx4 v[216:217], off
	v_lshl_add_u64 v[216:217], v[220:221], 0, s[30:31]
	s_mov_b32 m0, s65
	s_nop 0
	global_load_lds_dwordx4 v[216:217], off
	v_lshl_add_u64 v[216:217], v[222:223], 0, s[30:31]
	s_mov_b32 m0, s66
	s_nop 0
	global_load_lds_dwordx4 v[216:217], off
	s_waitcnt vmcnt(8)
	s_waitcnt lgkmcnt(0)
	s_setprio 1
	s_barrier
	v_mfma_f32_16x16x32_bf16 v[60:63], v[128:131], v[176:179], v[60:63]
	v_mfma_f32_16x16x32_bf16 v[56:59], v[136:139], v[176:179], v[56:59]
	v_mfma_f32_16x16x32_bf16 v[40:43], v[136:139], v[192:195], v[40:43]
	v_mfma_f32_16x16x32_bf16 v[44:47], v[128:131], v[192:195], v[44:47]
	v_mfma_f32_16x16x32_bf16 v[28:31], v[128:131], v[200:203], v[28:31]
	v_mfma_f32_16x16x32_bf16 v[24:27], v[136:139], v[200:203], v[24:27]
	v_mfma_f32_16x16x32_bf16 v[8:11], v[136:139], v[208:211], v[8:11]
	v_mfma_f32_16x16x32_bf16 v[12:15], v[128:131], v[208:211], v[12:15]
	v_mfma_f32_16x16x32_bf16 v[12:15], v[132:135], v[212:215], v[12:15]
	v_mfma_f32_16x16x32_bf16 v[8:11], v[140:143], v[212:215], v[8:11]
	v_mfma_f32_16x16x32_bf16 v[24:27], v[140:143], v[204:207], v[24:27]
	v_mfma_f32_16x16x32_bf16 v[28:31], v[132:135], v[204:207], v[28:31]
	v_mfma_f32_16x16x32_bf16 v[44:47], v[132:135], v[196:199], v[44:47]
	v_mfma_f32_16x16x32_bf16 v[40:43], v[140:143], v[196:199], v[40:43]
	v_mfma_f32_16x16x32_bf16 v[56:59], v[140:143], v[188:191], v[56:59]
	v_mfma_f32_16x16x32_bf16 v[60:63], v[132:135], v[188:191], v[60:63]
	v_mfma_f32_16x16x32_bf16 v[52:55], v[144:147], v[176:179], v[52:55]
	v_mfma_f32_16x16x32_bf16 v[48:51], v[152:155], v[176:179], v[48:51]
	v_mfma_f32_16x16x32_bf16 v[32:35], v[152:155], v[192:195], v[32:35]
	v_mfma_f32_16x16x32_bf16 v[36:39], v[144:147], v[192:195], v[36:39]
	v_mfma_f32_16x16x32_bf16 v[20:23], v[144:147], v[200:203], v[20:23]
	v_mfma_f32_16x16x32_bf16 v[16:19], v[152:155], v[200:203], v[16:19]
	v_mfma_f32_16x16x32_bf16 v[0:3], v[152:155], v[208:211], v[0:3]
	v_mfma_f32_16x16x32_bf16 v[4:7], v[144:147], v[208:211], v[4:7]
	v_mfma_f32_16x16x32_bf16 v[4:7], v[148:151], v[212:215], v[4:7]
	v_mfma_f32_16x16x32_bf16 v[0:3], v[156:159], v[212:215], v[0:3]
	v_mfma_f32_16x16x32_bf16 v[16:19], v[156:159], v[204:207], v[16:19]
	v_mfma_f32_16x16x32_bf16 v[20:23], v[148:151], v[204:207], v[20:23]
	v_mfma_f32_16x16x32_bf16 v[36:39], v[148:151], v[196:199], v[36:39]
	v_mfma_f32_16x16x32_bf16 v[32:35], v[156:159], v[196:199], v[32:35]
	v_mfma_f32_16x16x32_bf16 v[48:51], v[156:159], v[188:191], v[48:51]
	v_mfma_f32_16x16x32_bf16 v[52:55], v[148:151], v[188:191], v[52:55]
	s_barrier
	s_setprio 0
	s_add_i32 s78, s78, 2
	s_add_u32 s54, s54, 0x100
	s_addc_u32 s55, s55, 0
	s_add_u32 s76, s76, 0x100
	s_addc_u32 s77, s77, 0
	s_cmp_gt_u32 s78, 61
	s_cbranch_scc0 .LBB0_840
	s_and_b64 vcc, exec, s[34:35]
	s_cbranch_vccz .LBB0_843
	s_barrier

.LBB0_887:
	ds_read_b128 v[72:75], v175
	ds_read_b128 v[76:79], v175 offset:1024
	ds_read_b128 v[80:83], v175 offset:2048
	ds_read_b128 v[84:87], v175 offset:3072
	ds_read_b128 v[160:163], v176
	ds_read_b128 v[164:167], v176 offset:1024
	ds_read_b128 v[168:171], v176 offset:2048
	ds_read_b128 v[178:181], v176 offset:3072
	s_add_u32 s14, s48, 0xffc00080
	s_addc_u32 s15, s49, -1
	s_cmpk_eq_i32 s66, 0xfc
	s_cselect_b32 s53, s39, s15
	s_cselect_b32 s52, s62, s14
	s_cselect_b32 s51, s41, s65
	s_cselect_b32 s50, s63, s64
	v_lshl_add_u64 v[214:215], s[48:49], 0, v[152:153]
	s_add_i32 m0, s47, 0xc000
	ds_read_b128 v[182:185], v177
	ds_read_b128 v[186:189], v177 offset:1024
	ds_read_b128 v[190:193], v177 offset:2048
	ds_read_b128 v[194:197], v177 offset:3072
	ds_read_b128 v[198:201], v177 offset:4096
	ds_read_b128 v[202:205], v177 offset:5120
	ds_read_b128 v[206:209], v177 offset:6144
	ds_read_b128 v[210:213], v177 offset:7168
	global_load_lds_dwordx4 v[214:215], off
	v_lshl_add_u64 v[214:215], s[48:49], 0, v[154:155]
	s_add_i32 m0, s47, 0xe000
	s_nop 0
	global_load_lds_dwordx4 v[214:215], off
	s_waitcnt vmcnt(8)
	s_waitcnt lgkmcnt(0)
	s_setprio 1
	s_barrier
	v_mfma_f32_16x16x32_bf16 v[140:143], v[72:75], v[182:185], v[140:143]
	v_mfma_f32_16x16x32_bf16 v[136:139], v[80:83], v[182:185], v[136:139]
	v_mfma_f32_16x16x32_bf16 v[120:123], v[80:83], v[190:193], v[120:123]
	v_mfma_f32_16x16x32_bf16 v[124:127], v[72:75], v[190:193], v[124:127]
	v_mfma_f32_16x16x32_bf16 v[108:111], v[72:75], v[198:201], v[108:111]
	v_mfma_f32_16x16x32_bf16 v[104:107], v[80:83], v[198:201], v[104:107]
	v_mfma_f32_16x16x32_bf16 v[88:91], v[80:83], v[206:209], v[88:91]
	v_mfma_f32_16x16x32_bf16 v[92:95], v[72:75], v[206:209], v[92:95]
	v_mfma_f32_16x16x32_bf16 v[92:95], v[76:79], v[210:213], v[92:95]
	v_mfma_f32_16x16x32_bf16 v[88:91], v[84:87], v[210:213], v[88:91]
	v_mfma_f32_16x16x32_bf16 v[104:107], v[84:87], v[202:205], v[104:107]
	v_mfma_f32_16x16x32_bf16 v[108:111], v[76:79], v[202:205], v[108:111]
	v_mfma_f32_16x16x32_bf16 v[124:127], v[76:79], v[194:197], v[124:127]
	v_mfma_f32_16x16x32_bf16 v[120:123], v[84:87], v[194:197], v[120:123]
	v_mfma_f32_16x16x32_bf16 v[136:139], v[84:87], v[186:189], v[136:139]
	v_mfma_f32_16x16x32_bf16 v[140:143], v[76:79], v[186:189], v[140:143]
	v_mfma_f32_16x16x32_bf16 v[132:135], v[160:163], v[182:185], v[132:135]
	v_mfma_f32_16x16x32_bf16 v[128:131], v[168:171], v[182:185], v[128:131]
	v_mfma_f32_16x16x32_bf16 v[112:115], v[168:171], v[190:193], v[112:115]
	v_mfma_f32_16x16x32_bf16 v[116:119], v[160:163], v[190:193], v[116:119]
	v_mfma_f32_16x16x32_bf16 v[100:103], v[160:163], v[198:201], v[100:103]
	v_mfma_f32_16x16x32_bf16 v[96:99], v[168:171], v[198:201], v[96:99]
	v_mfma_f32_16x16x32_bf16 v[64:67], v[168:171], v[206:209], v[64:67]
	v_mfma_f32_16x16x32_bf16 v[68:71], v[160:163], v[206:209], v[68:71]
	v_mfma_f32_16x16x32_bf16 v[68:71], v[164:167], v[210:213], v[68:71]
	v_mfma_f32_16x16x32_bf16 v[64:67], v[178:181], v[210:213], v[64:67]
	v_mfma_f32_16x16x32_bf16 v[96:99], v[178:181], v[202:205], v[96:99]
	v_mfma_f32_16x16x32_bf16 v[100:103], v[164:167], v[202:205], v[100:103]
	v_mfma_f32_16x16x32_bf16 v[116:119], v[164:167], v[194:197], v[116:119]
	v_mfma_f32_16x16x32_bf16 v[112:115], v[178:181], v[194:197], v[112:115]
	v_mfma_f32_16x16x32_bf16 v[128:131], v[178:181], v[186:189], v[128:131]
	v_mfma_f32_16x16x32_bf16 v[132:135], v[164:167], v[186:189], v[132:135]
	s_barrier
	s_setprio 0
	s_add_i32 s14, s33, s54
	v_lshl_add_u64 v[214:215], s[50:51], 0, v[146:147]
	s_mov_b32 m0, s14
	ds_read_b128 v[182:185], v177 offset:16384
	ds_read_b128 v[186:189], v177 offset:17408
	ds_read_b128 v[190:193], v177 offset:18432
	ds_read_b128 v[194:197], v177 offset:19456
	ds_read_b128 v[198:201], v177 offset:20480
	ds_read_b128 v[202:205], v177 offset:21504
	ds_read_b128 v[206:209], v177 offset:22528
	ds_read_b128 v[210:213], v177 offset:23552
	global_load_lds_dwordx4 v[214:215], off
	s_add_i32 m0, s14, 0x2000
	s_add_u32 s14, s50, 0x400000
	v_lshl_add_u64 v[216:217], s[50:51], 0, v[150:151]
	s_addc_u32 s15, s51, 0
	s_add_i32 s67, s60, s54
	global_load_lds_dwordx4 v[216:217], off
	v_lshl_add_u64 v[218:219], s[14:15], 0, v[146:147]
	s_mov_b32 m0, s67
	v_lshl_add_u64 v[220:221], s[52:53], 0, v[148:149]
	global_load_lds_dwordx4 v[218:219], off
	v_lshl_add_u64 v[218:219], s[14:15], 0, v[150:151]
	s_add_i32 m0, s67, 0x2000
	s_nop 0
	global_load_lds_dwordx4 v[218:219], off
	v_lshl_add_u64 v[218:219], s[52:53], 0, v[144:145]
	s_mov_b32 m0, s47
	s_nop 0
	global_load_lds_dwordx4 v[218:219], off
	s_mov_b32 m0, s55
	s_nop 0
	global_load_lds_dwordx4 v[220:221], off
	s_waitcnt vmcnt(8)
	s_waitcnt lgkmcnt(0)
	s_setprio 1
	s_barrier
	v_mfma_f32_16x16x32_bf16 v[60:63], v[72:75], v[182:185], v[60:63]
	v_mfma_f32_16x16x32_bf16 v[56:59], v[80:83], v[182:185], v[56:59]
	v_mfma_f32_16x16x32_bf16 v[40:43], v[80:83], v[190:193], v[40:43]
	v_mfma_f32_16x16x32_bf16 v[44:47], v[72:75], v[190:193], v[44:47]
	v_mfma_f32_16x16x32_bf16 v[28:31], v[72:75], v[198:201], v[28:31]
	v_mfma_f32_16x16x32_bf16 v[24:27], v[80:83], v[198:201], v[24:27]
	v_mfma_f32_16x16x32_bf16 v[8:11], v[80:83], v[206:209], v[8:11]
	v_mfma_f32_16x16x32_bf16 v[12:15], v[72:75], v[206:209], v[12:15]
	v_mfma_f32_16x16x32_bf16 v[12:15], v[76:79], v[210:213], v[12:15]
	v_mfma_f32_16x16x32_bf16 v[8:11], v[84:87], v[210:213], v[8:11]
	v_mfma_f32_16x16x32_bf16 v[24:27], v[84:87], v[202:205], v[24:27]
	v_mfma_f32_16x16x32_bf16 v[28:31], v[76:79], v[202:205], v[28:31]
	v_mfma_f32_16x16x32_bf16 v[44:47], v[76:79], v[194:197], v[44:47]
	v_mfma_f32_16x16x32_bf16 v[40:43], v[84:87], v[194:197], v[40:43]
	v_mfma_f32_16x16x32_bf16 v[56:59], v[84:87], v[186:189], v[56:59]
	v_mfma_f32_16x16x32_bf16 v[60:63], v[76:79], v[186:189], v[60:63]
	v_mfma_f32_16x16x32_bf16 v[52:55], v[160:163], v[182:185], v[52:55]
	v_mfma_f32_16x16x32_bf16 v[48:51], v[168:171], v[182:185], v[48:51]
	v_mfma_f32_16x16x32_bf16 v[32:35], v[168:171], v[190:193], v[32:35]
	v_mfma_f32_16x16x32_bf16 v[36:39], v[160:163], v[190:193], v[36:39]
	v_mfma_f32_16x16x32_bf16 v[20:23], v[160:163], v[198:201], v[20:23]
	v_mfma_f32_16x16x32_bf16 v[16:19], v[168:171], v[198:201], v[16:19]
	v_mfma_f32_16x16x32_bf16 v[0:3], v[168:171], v[206:209], v[0:3]
	v_mfma_f32_16x16x32_bf16 v[4:7], v[160:163], v[206:209], v[4:7]
	v_mfma_f32_16x16x32_bf16 v[4:7], v[164:167], v[210:213], v[4:7]
	v_mfma_f32_16x16x32_bf16 v[0:3], v[178:181], v[210:213], v[0:3]
	v_mfma_f32_16x16x32_bf16 v[16:19], v[178:181], v[202:205], v[16:19]
	v_mfma_f32_16x16x32_bf16 v[20:23], v[164:167], v[202:205], v[20:23]
	v_mfma_f32_16x16x32_bf16 v[36:39], v[164:167], v[194:197], v[36:39]
	v_mfma_f32_16x16x32_bf16 v[32:35], v[178:181], v[194:197], v[32:35]
	v_mfma_f32_16x16x32_bf16 v[48:51], v[178:181], v[186:189], v[48:51]
	v_mfma_f32_16x16x32_bf16 v[52:55], v[164:167], v[186:189], v[52:55]
	s_barrier
	s_setprio 0
	s_add_i32 s67, 0, 0x18000
	s_add_i32 s68, 0, 0x1c000
	v_add_u32_e32 v84, s67, v173
	v_add_u32_e32 v178, s68, v173
	ds_read_b128 v[72:75], v84
	ds_read_b128 v[76:79], v84 offset:1024
	ds_read_b128 v[80:83], v84 offset:2048
	ds_read_b128 v[84:87], v84 offset:3072
	ds_read_b128 v[160:163], v178
	ds_read_b128 v[164:167], v178 offset:1024
	ds_read_b128 v[168:171], v178 offset:2048
	ds_read_b128 v[178:181], v178 offset:3072
	s_add_u32 s14, s52, 0x400000
	s_addc_u32 s15, s53, 0
	s_mov_b32 m0, s56
	v_lshl_add_u64 v[222:223], s[14:15], 0, v[144:145]
	ds_read_b128 v[182:185], v177 offset:32768
	ds_read_b128 v[186:189], v177 offset:33792
	ds_read_b128 v[190:193], v177 offset:34816
	ds_read_b128 v[194:197], v177 offset:35840
	ds_read_b128 v[198:201], v177 offset:36864
	ds_read_b128 v[202:205], v177 offset:37888
	ds_read_b128 v[206:209], v177 offset:38912
	ds_read_b128 v[210:213], v177 offset:39936
	global_load_lds_dwordx4 v[222:223], off
	v_lshl_add_u64 v[222:223], s[14:15], 0, v[148:149]
	s_mov_b32 m0, s57
	s_nop 0
	global_load_lds_dwordx4 v[222:223], off
	s_waitcnt vmcnt(8)
	s_waitcnt lgkmcnt(0)
	s_setprio 1
	s_barrier
	v_mfma_f32_16x16x32_bf16 v[140:143], v[72:75], v[182:185], v[140:143]
	v_mfma_f32_16x16x32_bf16 v[136:139], v[80:83], v[182:185], v[136:139]
	v_mfma_f32_16x16x32_bf16 v[120:123], v[80:83], v[190:193], v[120:123]
	v_mfma_f32_16x16x32_bf16 v[124:127], v[72:75], v[190:193], v[124:127]
	v_mfma_f32_16x16x32_bf16 v[108:111], v[72:75], v[198:201], v[108:111]
	v_mfma_f32_16x16x32_bf16 v[104:107], v[80:83], v[198:201], v[104:107]
	v_mfma_f32_16x16x32_bf16 v[88:91], v[80:83], v[206:209], v[88:91]
	v_mfma_f32_16x16x32_bf16 v[92:95], v[72:75], v[206:209], v[92:95]
	v_mfma_f32_16x16x32_bf16 v[92:95], v[76:79], v[210:213], v[92:95]
	v_mfma_f32_16x16x32_bf16 v[88:91], v[84:87], v[210:213], v[88:91]
	v_mfma_f32_16x16x32_bf16 v[104:107], v[84:87], v[202:205], v[104:107]
	v_mfma_f32_16x16x32_bf16 v[108:111], v[76:79], v[202:205], v[108:111]
	v_mfma_f32_16x16x32_bf16 v[124:127], v[76:79], v[194:197], v[124:127]
	v_mfma_f32_16x16x32_bf16 v[120:123], v[84:87], v[194:197], v[120:123]
	v_mfma_f32_16x16x32_bf16 v[136:139], v[84:87], v[186:189], v[136:139]
	v_mfma_f32_16x16x32_bf16 v[140:143], v[76:79], v[186:189], v[140:143]
	v_mfma_f32_16x16x32_bf16 v[132:135], v[160:163], v[182:185], v[132:135]
	v_mfma_f32_16x16x32_bf16 v[128:131], v[168:171], v[182:185], v[128:131]
	v_mfma_f32_16x16x32_bf16 v[112:115], v[168:171], v[190:193], v[112:115]
	v_mfma_f32_16x16x32_bf16 v[116:119], v[160:163], v[190:193], v[116:119]
	v_mfma_f32_16x16x32_bf16 v[100:103], v[160:163], v[198:201], v[100:103]
	v_mfma_f32_16x16x32_bf16 v[96:99], v[168:171], v[198:201], v[96:99]
	v_mfma_f32_16x16x32_bf16 v[64:67], v[168:171], v[206:209], v[64:67]
	v_mfma_f32_16x16x32_bf16 v[68:71], v[160:163], v[206:209], v[68:71]
	v_mfma_f32_16x16x32_bf16 v[68:71], v[164:167], v[210:213], v[68:71]
	v_mfma_f32_16x16x32_bf16 v[64:67], v[178:181], v[210:213], v[64:67]
	v_mfma_f32_16x16x32_bf16 v[96:99], v[178:181], v[202:205], v[96:99]
	v_mfma_f32_16x16x32_bf16 v[100:103], v[164:167], v[202:205], v[100:103]
	v_mfma_f32_16x16x32_bf16 v[116:119], v[164:167], v[194:197], v[116:119]
	v_mfma_f32_16x16x32_bf16 v[112:115], v[178:181], v[194:197], v[112:115]
	v_mfma_f32_16x16x32_bf16 v[128:131], v[178:181], v[186:189], v[128:131]
	v_mfma_f32_16x16x32_bf16 v[132:135], v[164:167], v[186:189], v[132:135]
	s_barrier
	s_setprio 0
	s_add_i32 s14, s67, s54
	v_lshl_add_u64 v[214:215], v[214:215], 0, s[30:31]
	s_mov_b32 m0, s14
	ds_read_b128 v[182:185], v177 offset:49152
	ds_read_b128 v[186:189], v177 offset:50176
	ds_read_b128 v[190:193], v177 offset:51200
	ds_read_b128 v[194:197], v177 offset:52224
	ds_read_b128 v[198:201], v177 offset:53248
	ds_read_b128 v[202:205], v177 offset:54272
	ds_read_b128 v[206:209], v177 offset:55296
	ds_read_b128 v[210:213], v177 offset:56320
	global_load_lds_dwordx4 v[214:215], off
	s_add_i32 m0, s14, 0x2000
	s_add_u32 s14, s50, 0x400080
	v_lshl_add_u64 v[214:215], v[216:217], 0, s[30:31]
	s_addc_u32 s15, s51, 0
	s_add_i32 s50, s68, s54
	global_load_lds_dwordx4 v[214:215], off
	v_lshl_add_u64 v[214:215], s[14:15], 0, v[146:147]
	s_mov_b32 m0, s50
	s_nop 0
	global_load_lds_dwordx4 v[214:215], off
	v_lshl_add_u64 v[214:215], s[14:15], 0, v[150:151]
	s_add_i32 m0, s50, 0x2000
	s_nop 0
	global_load_lds_dwordx4 v[214:215], off
	v_lshl_add_u64 v[214:215], v[218:219], 0, s[30:31]
	s_mov_b32 m0, s58
	s_nop 0
	global_load_lds_dwordx4 v[214:215], off
	v_lshl_add_u64 v[214:215], v[220:221], 0, s[30:31]
	s_mov_b32 m0, s59
	s_nop 0
	global_load_lds_dwordx4 v[214:215], off
	s_waitcnt vmcnt(8)
	s_waitcnt lgkmcnt(0)
	s_setprio 1
	s_barrier
	v_mfma_f32_16x16x32_bf16 v[60:63], v[72:75], v[182:185], v[60:63]
	v_mfma_f32_16x16x32_bf16 v[56:59], v[80:83], v[182:185], v[56:59]
	v_mfma_f32_16x16x32_bf16 v[40:43], v[80:83], v[190:193], v[40:43]
	v_mfma_f32_16x16x32_bf16 v[44:47], v[72:75], v[190:193], v[44:47]
	v_mfma_f32_16x16x32_bf16 v[28:31], v[72:75], v[198:201], v[28:31]
	v_mfma_f32_16x16x32_bf16 v[24:27], v[80:83], v[198:201], v[24:27]
	v_mfma_f32_16x16x32_bf16 v[8:11], v[80:83], v[206:209], v[8:11]
	v_mfma_f32_16x16x32_bf16 v[12:15], v[72:75], v[206:209], v[12:15]
	v_mfma_f32_16x16x32_bf16 v[12:15], v[76:79], v[210:213], v[12:15]
	v_mfma_f32_16x16x32_bf16 v[8:11], v[84:87], v[210:213], v[8:11]
	v_mfma_f32_16x16x32_bf16 v[24:27], v[84:87], v[202:205], v[24:27]
	v_mfma_f32_16x16x32_bf16 v[28:31], v[76:79], v[202:205], v[28:31]
	v_mfma_f32_16x16x32_bf16 v[44:47], v[76:79], v[194:197], v[44:47]
	v_mfma_f32_16x16x32_bf16 v[40:43], v[84:87], v[194:197], v[40:43]
	v_mfma_f32_16x16x32_bf16 v[56:59], v[84:87], v[186:189], v[56:59]
	v_mfma_f32_16x16x32_bf16 v[60:63], v[76:79], v[186:189], v[60:63]
	v_mfma_f32_16x16x32_bf16 v[52:55], v[160:163], v[182:185], v[52:55]
	v_mfma_f32_16x16x32_bf16 v[48:51], v[168:171], v[182:185], v[48:51]
	v_mfma_f32_16x16x32_bf16 v[32:35], v[168:171], v[190:193], v[32:35]
	v_mfma_f32_16x16x32_bf16 v[36:39], v[160:163], v[190:193], v[36:39]
	v_mfma_f32_16x16x32_bf16 v[20:23], v[160:163], v[198:201], v[20:23]
	v_mfma_f32_16x16x32_bf16 v[16:19], v[168:171], v[198:201], v[16:19]
	v_mfma_f32_16x16x32_bf16 v[0:3], v[168:171], v[206:209], v[0:3]
	v_mfma_f32_16x16x32_bf16 v[4:7], v[160:163], v[206:209], v[4:7]
	v_mfma_f32_16x16x32_bf16 v[4:7], v[164:167], v[210:213], v[4:7]
	v_mfma_f32_16x16x32_bf16 v[0:3], v[178:181], v[210:213], v[0:3]
	v_mfma_f32_16x16x32_bf16 v[16:19], v[178:181], v[202:205], v[16:19]
	v_mfma_f32_16x16x32_bf16 v[20:23], v[164:167], v[202:205], v[20:23]
	v_mfma_f32_16x16x32_bf16 v[36:39], v[164:167], v[194:197], v[36:39]
	v_mfma_f32_16x16x32_bf16 v[32:35], v[178:181], v[194:197], v[32:35]
	v_mfma_f32_16x16x32_bf16 v[48:51], v[178:181], v[186:189], v[48:51]
	v_mfma_f32_16x16x32_bf16 v[52:55], v[164:167], v[186:189], v[52:55]
	s_barrier
	s_setprio 0
	s_add_i32 s66, s66, 2
	s_add_u32 s48, s48, 0x100
	s_addc_u32 s49, s49, 0
	s_add_u32 s64, s64, 0x100
	s_addc_u32 s65, s65, 0
	s_cmpk_gt_u32 s66, 0xfd
	s_cbranch_scc0 .LBB0_887
	s_and_b64 vcc, exec, s[34:35]
	s_cbranch_vccz .LBB0_890
	s_barrier
